# v27 + MLA tile body: K/V fragment LDS addresses carried across tiles (toggled at body end)
# baseline (speedup 1.0000x reference)
; template <int DQ, bool NA, int NQG>
; DI void attn_wg(const half_t* Qp, const half_t* Kp, const half_t* Vp, int q0, bool active, int seg0_start, int seg0_tiles,
;                 int seg1_start, int seg1_tiles, const float* rpb_h, int rq, char* smem, int tid, f16v (&O)[2][NQG]) {
;     ...
;   float mrun[NQG], lrun[NQG];
; #pragma unroll
;   for (int qg = 0; qg < NQG; ++qg) { mrun[qg] = -1e30f; lrun[qg] = 0.f; }
; #pragma unroll
;   for (int a = 0; a < 2; ++a)
; #pragma unroll
;     for (int c = 0; c < NQG; ++c)
; #pragma unroll
;       for (int i = 0; i < 16; ++i) O[a][c][i] = 0.f;
;   const int ntiles = seg0_tiles + seg1_tiles;
;   const int kc0 = tid, kc1 = tid + 512;
;   const half_t* kg0 = Kp + kc0 * 8;
;   const half_t* kg1 = Kp + kc1 * 8;
;   const half_t* vg = Vp + (size_t)(tid >> 3) * TOK + (tid & 7) * 8;
;   const int ks0 = (kc0 / CPK) * KSTR + (kc0 % CPK) * 8, ks1 = (kc1 / CPK) * KSTR + (kc1 % CPK) * 8, vs0 = (tid >> 3) * VSTR + (tid & 7) * 8;
;   uint4 kreg0 = {0, 0, 0, 0}, kreg1 = {0, 0, 0, 0}, vreg;
;   const int r0w = min(max(rq - 4, 0), 24);
;   {
;     const int k0 = (0 < seg0_tiles) ? seg0_start : seg1_start;
;     if (kc0 < KCH) kreg0 = *(const uint4*)(kg0 + (size_t)k0 * DQ);
;     if (DQ == 96 && kc1 < KCH) kreg1 = *(const uint4*)(kg1 + (size_t)k0 * DQ);
;     vreg = *(const uint4*)(vg + k0);
;     if (kc0 < KCH) *(uint4*)((half_t*)smem + ks0) = kreg0;
;     if (DQ == 96 && kc1 < KCH) *(uint4*)((half_t*)smem + ks1) = kreg1;
;     *(uint4*)((half_t*)(smem + ATT_VOFF) + vs0) = vreg;
;   }
;   __syncthreads();
;     ...
;     const half_t* ksm = (const half_t*)(smem + (it & 1) * ATT_STAGE) + r * KSTR + h * 8;
;     const half_t* vsm = (const half_t*)(smem + (it & 1) * ATT_STAGE + ATT_VOFF) + r * VSTR + h * 4;
.LBB0_2185:
	s_or_b64 exec, exec, s[8:9]
	v_mov_b32_e32 v14, v0
	v_mov_b32_e32 v15, v0
	v_mov_b32_e32 v1, v0
	v_mov_b32_e32 v2, v0
	v_mov_b32_e32 v3, v0
	v_mov_b32_e32 v4, v0
	v_mov_b32_e32 v5, v0
	v_mov_b32_e32 v6, v0
	v_mov_b32_e32 v7, v0
	v_mov_b32_e32 v8, v0
	v_mov_b32_e32 v9, v0
	v_mov_b32_e32 v10, v0
	v_mov_b32_e32 v11, v0
	v_mov_b32_e32 v12, v0
	v_mov_b32_e32 v13, v0
	v_mov_b64_e32 v[64:65], v[14:15]
	v_mov_b64_e32 v[32:33], v[14:15]
	v_mov_b64_e32 v[48:49], v[14:15]
	s_and_b64 s[8:9], s[20:21], exec
	v_mov_b64_e32 v[62:63], v[12:13]
	v_mov_b64_e32 v[60:61], v[10:11]
	v_mov_b64_e32 v[58:59], v[8:9]
	v_mov_b64_e32 v[56:57], v[6:7]
	v_mov_b64_e32 v[54:55], v[4:5]
	v_mov_b64_e32 v[52:53], v[2:3]
	v_mov_b64_e32 v[50:51], v[0:1]
	v_mov_b64_e32 v[30:31], v[12:13]
	v_mov_b64_e32 v[28:29], v[10:11]
	v_mov_b64_e32 v[26:27], v[8:9]
	v_mov_b64_e32 v[24:25], v[6:7]
	v_mov_b64_e32 v[22:23], v[4:5]
	v_mov_b64_e32 v[20:21], v[2:3]
	v_mov_b64_e32 v[18:19], v[0:1]
	v_mov_b64_e32 v[46:47], v[12:13]
	v_mov_b64_e32 v[44:45], v[10:11]
	v_mov_b64_e32 v[42:43], v[8:9]
	v_mov_b64_e32 v[40:41], v[6:7]
	v_mov_b64_e32 v[38:39], v[4:5]
	v_mov_b64_e32 v[36:37], v[2:3]
	v_mov_b64_e32 v[34:35], v[0:1]
	v_mov_b64_e32 v[16:17], v[14:15]
	s_cselect_b32 s27, 36, 4
	s_mov_b32 s24, 0
	v_mov_b32_e32 v210, 0xf149f2ca
	v_mov_b32_e32 v199, 0
	v_mov_b64_e32 v[14:15], v[12:13]
	v_mov_b64_e32 v[12:13], v[10:11]
	v_mov_b64_e32 v[10:11], v[8:9]
	v_mov_b64_e32 v[8:9], v[6:7]
	v_mov_b64_e32 v[6:7], v[4:5]
	v_mov_b64_e32 v[4:5], v[2:3]
	v_mov_b64_e32 v[2:3], v[0:1]
	v_mov_b32_e32 v1, 0
	v_mov_b32_e32 v212, 0xf149f2ca
	s_waitcnt vmcnt(0)
	ds_write_b128 v185, v[154:157] offset:13312
	s_waitcnt lgkmcnt(0)
	s_barrier
	v_mul_u32_u24_e32 v211, 0xd0, v174
	v_add3_u32 v211, 0, v211, v180
	v_mul_u32_u24_e32 v213, 0x90, v174
	v_add3_u32 v213, 0, v213, v175
	v_add_u32_e32 v243, 0x4600, v213
	v_add_u32_e32 v213, 0x3400, v213

; template <int DQ, bool NA, int NQG>
; DI void attn_wg(const half_t* Qp, const half_t* Kp, const half_t* Vp, int q0, bool active, int seg0_start, int seg0_tiles,
;                 int seg1_start, int seg1_tiles, const float* rpb_h, int rq, char* smem, int tid, f16v (&O)[2][NQG]) {
;     ...
;     if (need) {
; #pragma unroll 1
;       for (int st = 0; st < 2; ++st) {
;         f16v S[NQG];
; #pragma unroll
;         for (int qg = 0; qg < NQG; ++qg)
; #pragma unroll
;           for (int i = 0; i < 16; ++i) S[qg][i] = 0.f;
; #pragma unroll
;         for (int ks = 0; ks < NKS; ++ks) {
;           const h8 kf = *(const h8*)(ksm + (st * 32) * KSTR + ks * 16);
; #pragma unroll
;           for (int qg = 0; qg < NQG; ++qg) S[qg] = __builtin_amdgcn_mfma_f32_32x32x16_f16(kf, qf[qg][ks], S[qg], 0, 0, 0);
;         }
;         if (masked) {
;           const int cb = st * 32;
;           const int dr = krow - rq + 7;
; #pragma unroll
;           for (int qg = 0; qg < NQG; ++qg) {
;             const int qc = qg * 32 + r;
;             const int cs = min(max(qc - 8, 0), 48);
; #pragma unroll
;             for (int i = 0; i < 16; ++i) {
;               const int c = cb + (i & 3) + 8 * (i >> 2) + 4 * h;
;               const bool valid = (c >= cs) && (c < cs + 16);
;               float bias = 0.f;
;               if (valid) bias = rpb_h[dr * 31 + (c - qc + 15)] * LOG2E;
;               S[qg][i] = valid ? S[qg][i] + bias : -1e30f;
;             }
;           }
;         }
;         h4 vf[2][2][2];
; #pragma unroll
;         for (int dvt = 0; dvt < 2; ++dvt)
; #pragma unroll
;           for (int sx = 0; sx < 2; ++sx)
; #pragma unroll
;             for (int hf = 0; hf < 2; ++hf) vf[dvt][sx][hf] = *(const h4*)(vsm + (dvt * 32) * VSTR + st * 32 + sx * 16 + hf * 8);
; #pragma unroll
;         for (int qg = 0; qg < NQG; ++qg) {
;           h8 P[2];
;           float mx = S[qg][0];
; #pragma unroll
;           for (int i = 1; i < 16; ++i) mx = fmaxf(mx, S[qg][i]);
;           mx = fmaxf(mx, __shfl_xor(mx, 32));
;           if (__builtin_amdgcn_ballot_w64(mx > mrun[qg] + 8.f) != 0ull) {
;             const float mnew = fmaxf(mrun[qg], mx);
;             const float alpha = __builtin_amdgcn_exp2f(mrun[qg] - mnew);
.LBB0_2192:
	v_cndmask_b32_e64 v66, 0, 1, s[18:19]
	v_cmp_ne_u32_e64 s[8:9], 1, v66
	s_andn2_b64 vcc, exec, s[18:19]
	s_cbranch_vccnz .LBB0_2199
	s_bitcmp1_b32 s24, 0
	s_cselect_b32 s24, 0x5800, 0
	ds_read_b128 v[214:217], v211 offset:0
	ds_read_b128 v[218:221], v211 offset:32
	ds_read_b128 v[248:251], v211 offset:64
	ds_read2_b64 v[158:161], v213 offset0:0 offset1:2
	ds_read2_b64 v[162:165], v213 offset0:4 offset1:6
	ds_read2_b64 v[166:169], v243 offset0:0 offset1:2
	ds_read2_b64 v[170:173], v243 offset0:4 offset1:6
	s_waitcnt lgkmcnt(6)
	v_mfma_f32_32x32x16_f16 v[82:97], v[214:217], v[98:101], 0
	ds_read_b128 v[214:217], v211 offset:96
	s_waitcnt lgkmcnt(6)
	v_mfma_f32_32x32x16_f16 v[82:97], v[218:221], v[102:105], v[82:97]
	ds_read_b128 v[218:221], v211 offset:128
	s_waitcnt lgkmcnt(6)
	v_mfma_f32_32x32x16_f16 v[82:97], v[248:251], v[106:109], v[82:97]
	ds_read_b128 v[248:251], v211 offset:160
	s_waitcnt lgkmcnt(2)
	v_mfma_f32_32x32x16_f16 v[82:97], v[214:217], v[110:113], v[82:97]
	ds_read_b128 v[214:217], v211 offset:0
	s_waitcnt lgkmcnt(2)
	v_mfma_f32_32x32x16_f16 v[82:97], v[218:221], v[114:117], v[82:97]
	ds_read_b128 v[218:221], v211 offset:32
	s_waitcnt lgkmcnt(2)
	v_mfma_f32_32x32x16_f16 v[82:97], v[248:251], v[118:121], v[82:97]
	ds_read_b128 v[248:251], v211 offset:64
	s_nop 10
	v_max3_f32 v201, v82, v83, v84
	v_max3_f32 v203, v85, v86, v87
	v_max3_f32 v201, v201, v88, v89
	v_max3_f32 v203, v203, v90, v91
	v_max3_f32 v201, v201, v92, v93
	s_waitcnt lgkmcnt(2)
	v_mfma_f32_32x32x16_f16 v[66:81], v[214:217], v[122:125], 0
	ds_read_b128 v[214:217], v211 offset:96
	v_max3_f32 v203, v203, v94, v95
	v_max3_f32 v201, v201, v96, v97
	v_max_f32_e32 v201, v201, v203
	v_mov_b32_e32 v203, v201
	s_nop 1
	v_permlane32_swap_b32_e32 v203, v201
	v_max_f32_e32 v201, v201, v203
	v_add_f32_e32 v203, 0x41000000, v210
	s_waitcnt lgkmcnt(2)
	v_mfma_f32_32x32x16_f16 v[66:81], v[218:221], v[126:129], v[66:81]
	ds_read_b128 v[218:221], v211 offset:128
	v_cmp_gt_f32_e32 vcc, v201, v203
	s_cbranch_vccnz .Lresc_mla_0

; template <int DQ, bool NA, int NQG>
; DI void attn_wg(const half_t* Qp, const half_t* Kp, const half_t* Vp, int q0, bool active, int seg0_start, int seg0_tiles,
;                 int seg1_start, int seg1_tiles, const float* rpb_h, int rq, char* smem, int tid, f16v (&O)[2][NQG]) {
;     ...
;           const float mn = mrun[qg];
;           f2 rs2 = {0.f, 0.f};
;           const f2 mn2 = {mn, mn};
; #pragma unroll
;           for (int i = 0; i < 16; i += 2) {
;             const f2 s2 = {S[qg][i], S[qg][i + 1]};
;             const f2 d2 = s2 - mn2;
;             f2 p2;
;             p2.x = __builtin_amdgcn_exp2f(d2.x);
;             p2.y = __builtin_amdgcn_exp2f(d2.y);
;             if (NA) { p2.x = (s2.x <= -1e29f) ? 0.f : p2.x; p2.y = (s2.y <= -1e29f) ? 0.f : p2.y; }
;             rs2 += p2;
;             P[i >> 3][i & 7] = (half_t)p2.x;
;             P[i >> 3][(i & 7) + 1] = (half_t)p2.y;
;           }
;           lrun[qg] += rs2.x + rs2.y;
; #pragma unroll
;           for (int dvt = 0; dvt < 2; ++dvt) {
; #pragma unroll
;             for (int sx = 0; sx < 2; ++sx) {
;               const h8 va = __builtin_shufflevector(vf[dvt][sx][0], vf[dvt][sx][1], 0, 1, 2, 3, 4, 5, 6, 7);
;               O[dvt][qg] = __builtin_amdgcn_mfma_f32_32x32x16_f16(va, P[sx], O[dvt][qg], 0, 0, 0);
;             }
.Lcont_mla_3:
	v_pk_add_f32 v[66:67], v[66:67], v[212:213] op_sel_hi:[1,0] neg_lo:[0,1] neg_hi:[0,1]
	v_pk_add_f32 v[68:69], v[68:69], v[212:213] op_sel_hi:[1,0] neg_lo:[0,1] neg_hi:[0,1]
	v_exp_f32_e32 v66, v66
	v_exp_f32_e32 v67, v67
	v_pk_add_f32 v[70:71], v[70:71], v[212:213] op_sel_hi:[1,0] neg_lo:[0,1] neg_hi:[0,1]
	v_mfma_f32_32x32x16_f16 v[2:17], v[162:165], v[226:229], v[2:17]
	v_exp_f32_e32 v68, v68
	v_exp_f32_e32 v69, v69
	v_pk_add_f32 v[72:73], v[72:73], v[212:213] op_sel_hi:[1,0] neg_lo:[0,1] neg_hi:[0,1]
	v_exp_f32_e32 v70, v70
	v_exp_f32_e32 v71, v71
	v_pk_add_f32 v[74:75], v[74:75], v[212:213] op_sel_hi:[1,0] neg_lo:[0,1] neg_hi:[0,1]
	v_exp_f32_e32 v72, v72
	v_mfma_f32_32x32x16_f16 v[18:33], v[170:173], v[226:229], v[18:33]
	v_exp_f32_e32 v73, v73
	v_pk_add_f32 v[76:77], v[76:77], v[212:213] op_sel_hi:[1,0] neg_lo:[0,1] neg_hi:[0,1]
	v_exp_f32_e32 v74, v74
	v_exp_f32_e32 v75, v75
	v_pk_add_f32 v[78:79], v[78:79], v[212:213] op_sel_hi:[1,0] neg_lo:[0,1] neg_hi:[0,1]
	v_exp_f32_e32 v76, v76
	v_exp_f32_e32 v77, v77
	v_pk_add_f32 v[80:81], v[80:81], v[212:213] op_sel_hi:[1,0] neg_lo:[0,1] neg_hi:[0,1]
	v_exp_f32_e32 v78, v78
	v_exp_f32_e32 v79, v79
	v_exp_f32_e32 v80, v80
	v_exp_f32_e32 v81, v81
	v_cvt_pk_f16_f32 v222, v66, v67
	v_cvt_pk_f16_f32 v223, v68, v69
	v_cvt_pk_f16_f32 v224, v70, v71
	v_cvt_pk_f16_f32 v225, v72, v73
	v_cvt_pk_f16_f32 v226, v74, v75
	v_cvt_pk_f16_f32 v227, v76, v77
	v_cvt_pk_f16_f32 v228, v78, v79
	v_cvt_pk_f16_f32 v229, v80, v81
	v_pk_add_f32 v[66:67], v[66:67], v[68:69]
	v_pk_add_f32 v[70:71], v[70:71], v[72:73]
	v_pk_add_f32 v[74:75], v[74:75], v[76:77]
	v_pk_add_f32 v[78:79], v[78:79], v[80:81]
	v_pk_add_f32 v[66:67], v[66:67], v[70:71]
	v_pk_add_f32 v[74:75], v[74:75], v[78:79]
	v_pk_add_f32 v[66:67], v[66:67], v[74:75]
	v_add_f32_e32 v66, v66, v67
	v_add_f32_e32 v1, v1, v66
	v_mfma_f32_32x32x16_f16 v[34:49], v[158:161], v[222:225], v[34:49]
	v_mfma_f32_32x32x16_f16 v[50:65], v[166:169], v[222:225], v[50:65]
	v_mfma_f32_32x32x16_f16 v[34:49], v[162:165], v[226:229], v[34:49]
	v_mfma_f32_32x32x16_f16 v[50:65], v[170:173], v[226:229], v[50:65]
	s_lshl_b32 s40, s24, 1
	s_sub_u32 s40, 0x5800, s40
	v_add_u32_e32 v211, s40, v211
	v_add_u32_e32 v213, s40, v213
	v_add_u32_e32 v243, s40, v243
	s_branch .Lend_mla
